# ml_p1 gates: the two volatile-LDS scans (24 serialised FLAT round trips) replaced by DPP wave scans (on top of the v80 stack)
# baseline (speedup 1.0000x reference)
; __device__ __forceinline__ float bflo(unsigned u) { return __uint_as_float(u << 16); }
; __device__ __forceinline__ float bfhi(unsigned u) { return __uint_as_float(u & 0xffff0000u); }
; __device__ __forceinline__ void ml_p1_item(const Params& p, int l, int item, char* ldsraw) {
;     ...
; #pragma unroll
;     for (int i = 0; i < 2; i++) {
;       const int ci = tid + 256 * i; const int row = ci >> 3, c8 = ci & 7;
;       const u32x4 w = *(const u32x4*)(P + (size_t)(tokb + row) * PIN + C_ML + 256 + h * 64 + c8 * 8);
;       *(f32x4*)(Vs + row * 64 + c8 * 8) = (f32x4){bflo(w[0]), bfhi(w[0]), bflo(w[1]), bfhi(w[1])};
;       *(f32x4*)(Vs + row * 64 + c8 * 8 + 4) = (f32x4){bflo(w[2]), bfhi(w[2]), bflo(w[3]), bfhi(w[3])};
;     }
;     __syncthreads();
;     const int t = tid >> 2, dq = tid & 3;
; #pragma unroll
;     for (int i = 0; i < 8; i++) { int d = dq * 8 + i; Ks[t * 33 + d] = ml_conv_lds(raw, wl, t, 32 + d); }
.LBB0_553:
	s_or_b64 exec, exec, s[26:27]
	v_ashrrev_i32_e32 v20, 3, v0
	v_add_u32_e32 v4, s3, v20
	v_mov_b64_e32 v[12:13], s[28:29]
	v_lshlrev_b32_e32 v1, 3, v0
	v_mad_i64_i32 v[4:5], s[26:27], v4, s69, v[12:13]
	v_and_b32_e32 v2, 56, v1
	s_lshl_b32 s26, s2, 7
	s_mov_b32 s27, s89
	v_lshl_add_u32 v14, v2, 2, 0
	v_lshl_add_u64 v[4:5], v[4:5], 0, s[26:27]
	v_lshlrev_b32_e32 v2, 1, v2
	v_lshl_add_u64 v[4:5], v[4:5], 0, v[2:3]
	global_load_dwordx4 v[4:7], v[4:5], off offset:3456
	v_lshl_add_u32 v15, v20, 8, v14
	v_ashrrev_i32_e32 v22, 2, v0
	v_and_b32_e32 v1, 24, v1
	s_movk_i32 s4, 0x84
	v_cmp_gt_i32_e32 vcc, 64, v0
	s_waitcnt vmcnt(0)
	v_lshlrev_b32_e32 v8, 16, v4
	v_and_b32_e32 v9, 0xffff0000, v4
	v_lshlrev_b32_e32 v10, 16, v5
	v_and_b32_e32 v11, 0xffff0000, v5
	v_lshlrev_b32_e32 v4, 16, v6
	v_and_b32_e32 v5, 0xffff0000, v6
	v_lshlrev_b32_e32 v6, 16, v7
	v_and_b32_e32 v7, 0xffff0000, v7
	ds_write_b128 v15, v[4:7] offset:8464
	v_add_u32_e32 v4, 0x100, v0
	ds_write_b128 v15, v[8:11] offset:8448
	v_ashrrev_i32_e32 v15, 3, v4
	v_add_u32_e32 v4, s3, v15
	v_mad_i64_i32 v[4:5], s[30:31], v4, s69, v[12:13]
	v_lshl_add_u64 v[4:5], v[4:5], 0, s[26:27]
	v_lshl_add_u64 v[4:5], v[4:5], 0, v[2:3]
	global_load_dwordx4 v[4:7], v[4:5], off offset:3456
	v_lshl_add_u32 v2, v15, 8, v14
	s_waitcnt vmcnt(0)
	v_lshlrev_b32_e32 v8, 16, v4
	v_and_b32_e32 v9, 0xffff0000, v4
	v_lshlrev_b32_e32 v10, 16, v5
	v_and_b32_e32 v11, 0xffff0000, v5
	v_lshlrev_b32_e32 v4, 16, v6
	v_and_b32_e32 v5, 0xffff0000, v6
	v_lshlrev_b32_e32 v6, 16, v7
	v_and_b32_e32 v7, 0xffff0000, v7
	ds_write_b128 v2, v[8:11] offset:8448
	ds_write_b128 v2, v[4:7] offset:8464
	v_lshlrev_b32_e32 v4, 7, v22
	v_lshl_add_u32 v2, v1, 2, 0
	v_lshlrev_b32_e32 v1, 1, v1
	v_add3_u32 v1, 0, v4, v1
	s_waitcnt lgkmcnt(0)
	s_barrier
	ds_read_b128 v[4:7], v1 offset:25664
	ds_read_b128 v[12:15], v1 offset:25792
	ds_read_b32 v23, v2 offset:35328
	ds_read_b32 v9, v2 offset:34304
	ds_read_b128 v[16:19], v1 offset:25920
	s_waitcnt lgkmcnt(4)
	v_lshlrev_b32_e32 v8, 16, v4
	ds_read_b32 v24, v2 offset:35072
	v_and_b32_e32 v4, 0xffff0000, v4
	s_waitcnt lgkmcnt(2)
	v_fmac_f32_e32 v23, v9, v8
	ds_read_b32 v9, v2 offset:34560
	v_lshlrev_b32_e32 v8, 16, v12
	s_waitcnt lgkmcnt(0)
	v_fmac_f32_e32 v23, v9, v8
	ds_read_b32 v9, v2 offset:34816
	v_lshlrev_b32_e32 v8, 16, v16
	s_waitcnt lgkmcnt(0)
	v_fmac_f32_e32 v23, v9, v8
	ds_read_b128 v[8:11], v1 offset:26048
	s_waitcnt lgkmcnt(0)
	v_lshlrev_b32_e32 v1, 16, v8
	v_fmac_f32_e32 v23, v24, v1
	v_mul_f32_e32 v1, 0xbfb8aa3b, v23
	v_exp_f32_e32 v1, v1
	s_nop 0
	v_add_f32_e32 v1, 1.0, v1
	v_rcp_f32_e32 v1, v1
	s_nop 0
	v_mul_f32_e32 v1, v23, v1
	v_mad_u64_u32 v[22:23], s[26:27], v22, s4, v[2:3]
	ds_write_b32 v22, v1
	ds_read_b32 v1, v2 offset:35332
	ds_read_b32 v23, v2 offset:34308
	s_waitcnt lgkmcnt(0)
	v_fmac_f32_e32 v1, v23, v4
	v_and_b32_e32 v4, 0xffff0000, v12
	ds_read_b32 v12, v2 offset:34564
	s_waitcnt lgkmcnt(0)
	v_fmac_f32_e32 v1, v12, v4
	ds_read_b32 v12, v2 offset:34820
	v_and_b32_e32 v4, 0xffff0000, v16
	v_mov_b32_e32 v16, 0
	s_waitcnt lgkmcnt(0)
	v_fmac_f32_e32 v1, v12, v4
	v_and_b32_e32 v4, 0xffff0000, v8
	ds_read_b32 v8, v2 offset:35076
	s_waitcnt lgkmcnt(0)
	v_fmac_f32_e32 v1, v8, v4
	v_mul_f32_e32 v4, 0xbfb8aa3b, v1
	v_exp_f32_e32 v4, v4
	s_nop 0
	v_add_f32_e32 v4, 1.0, v4
	v_rcp_f32_e32 v4, v4
	s_nop 0
	v_mul_f32_e32 v1, v1, v4
	ds_write_b32 v22, v1 offset:4
	ds_read_b32 v1, v2 offset:35336
	ds_read_b32 v8, v2 offset:34312
	v_lshlrev_b32_e32 v4, 16, v5
	s_waitcnt lgkmcnt(0)
	v_fmac_f32_e32 v1, v8, v4
	ds_read_b32 v8, v2 offset:34568
	v_lshlrev_b32_e32 v4, 16, v13
	s_waitcnt lgkmcnt(0)
	v_fmac_f32_e32 v1, v8, v4
	ds_read_b32 v8, v2 offset:34824
	v_lshlrev_b32_e32 v4, 16, v17
	s_waitcnt lgkmcnt(0)
	v_fmac_f32_e32 v1, v8, v4
	ds_read_b32 v8, v2 offset:35080
	v_lshlrev_b32_e32 v4, 16, v9
	s_waitcnt lgkmcnt(0)
	v_fmac_f32_e32 v1, v8, v4
	v_mul_f32_e32 v4, 0xbfb8aa3b, v1
	v_exp_f32_e32 v4, v4
	s_nop 0
	v_add_f32_e32 v4, 1.0, v4
	v_rcp_f32_e32 v4, v4
	s_nop 0
	v_mul_f32_e32 v1, v1, v4
	ds_write_b32 v22, v1 offset:8
	ds_read_b32 v1, v2 offset:35340
	v_and_b32_e32 v4, 0xffff0000, v5
	ds_read_b32 v5, v2 offset:34316
	s_waitcnt lgkmcnt(0)
	v_fmac_f32_e32 v1, v5, v4
	ds_read_b32 v5, v2 offset:34572
	v_and_b32_e32 v4, 0xffff0000, v13
	s_waitcnt lgkmcnt(0)
	v_fmac_f32_e32 v1, v5, v4
	ds_read_b32 v5, v2 offset:34828
	v_and_b32_e32 v4, 0xffff0000, v17
	v_mov_b32_e32 v17, 0
	s_waitcnt lgkmcnt(0)
	v_fmac_f32_e32 v1, v5, v4
	ds_read_b32 v5, v2 offset:35084
	v_and_b32_e32 v4, 0xffff0000, v9
	s_waitcnt lgkmcnt(0)
	v_fmac_f32_e32 v1, v5, v4
	v_mul_f32_e32 v4, 0xbfb8aa3b, v1
	v_exp_f32_e32 v4, v4
	s_nop 0
	v_add_f32_e32 v4, 1.0, v4
	v_rcp_f32_e32 v4, v4
	s_nop 0
	v_mul_f32_e32 v1, v1, v4
	ds_write_b32 v22, v1 offset:12
	ds_read_b32 v1, v2 offset:35344
	ds_read_b32 v5, v2 offset:34320
	v_lshlrev_b32_e32 v4, 16, v6
	s_waitcnt lgkmcnt(0)
	v_fmac_f32_e32 v1, v5, v4
	ds_read_b32 v5, v2 offset:34576
	v_lshlrev_b32_e32 v4, 16, v14
	s_waitcnt lgkmcnt(0)
	v_fmac_f32_e32 v1, v5, v4
	ds_read_b32 v5, v2 offset:34832
	v_lshlrev_b32_e32 v4, 16, v18
	s_waitcnt lgkmcnt(0)
	v_fmac_f32_e32 v1, v5, v4
	ds_read_b32 v5, v2 offset:35088
	v_lshlrev_b32_e32 v4, 16, v10
	s_waitcnt lgkmcnt(0)
	v_fmac_f32_e32 v1, v5, v4
	v_mul_f32_e32 v4, 0xbfb8aa3b, v1
	v_exp_f32_e32 v4, v4
	s_nop 0
	v_add_f32_e32 v4, 1.0, v4
	v_rcp_f32_e32 v4, v4
	s_nop 0
	v_mul_f32_e32 v1, v1, v4
	ds_write_b32 v22, v1 offset:16
	ds_read_b32 v1, v2 offset:35348
	ds_read_b32 v5, v2 offset:34324
	v_and_b32_e32 v4, 0xffff0000, v6
	s_waitcnt lgkmcnt(0)
	v_fmac_f32_e32 v1, v5, v4
	ds_read_b32 v5, v2 offset:34580
	v_and_b32_e32 v4, 0xffff0000, v14
	s_waitcnt lgkmcnt(0)
; __device__ __forceinline__ void ml_p1_item(const Params& p, int l, int item, char* ldsraw) {
;     ...
;     for (int i = 0; i < 8; i++) { int d = dq * 8 + i; Ks[t * 33 + d] = ml_conv_lds(raw, wl, t, 32 + d); }
;     ...
;   if (tid < 64) {
	v_fmac_f32_e32 v1, v5, v4
	ds_read_b32 v5, v2 offset:34836
	v_and_b32_e32 v4, 0xffff0000, v18
	s_waitcnt lgkmcnt(0)
	v_fmac_f32_e32 v1, v5, v4
	ds_read_b32 v5, v2 offset:35092
	v_and_b32_e32 v4, 0xffff0000, v10
	s_waitcnt lgkmcnt(0)
	v_fmac_f32_e32 v1, v5, v4
	v_mul_f32_e32 v4, 0xbfb8aa3b, v1
	v_exp_f32_e32 v4, v4
	s_nop 0
	v_add_f32_e32 v4, 1.0, v4
	v_rcp_f32_e32 v4, v4
	s_nop 0
	v_mul_f32_e32 v1, v1, v4
	ds_write_b32 v22, v1 offset:20
	ds_read_b32 v1, v2 offset:35352
	ds_read_b32 v5, v2 offset:34328
	v_lshlrev_b32_e32 v4, 16, v7
	s_waitcnt lgkmcnt(0)
	v_fmac_f32_e32 v1, v5, v4
	ds_read_b32 v5, v2 offset:34584
	v_lshlrev_b32_e32 v4, 16, v15
	s_waitcnt lgkmcnt(0)
	v_fmac_f32_e32 v1, v5, v4
	ds_read_b32 v5, v2 offset:34840
	v_lshlrev_b32_e32 v4, 16, v19
	s_waitcnt lgkmcnt(0)
	v_fmac_f32_e32 v1, v5, v4
	ds_read_b32 v5, v2 offset:35096
	v_lshlrev_b32_e32 v4, 16, v11
	s_waitcnt lgkmcnt(0)
	v_fmac_f32_e32 v1, v5, v4
	v_mul_f32_e32 v4, 0xbfb8aa3b, v1
	v_exp_f32_e32 v4, v4
	s_nop 0
	v_add_f32_e32 v4, 1.0, v4
	v_rcp_f32_e32 v4, v4
	s_nop 0
	v_mul_f32_e32 v1, v1, v4
	ds_write_b32 v22, v1 offset:24
	ds_read_b32 v1, v2 offset:35356
	ds_read_b32 v5, v2 offset:34332
	v_and_b32_e32 v4, 0xffff0000, v7
	s_waitcnt lgkmcnt(0)
	v_fmac_f32_e32 v1, v5, v4
	ds_read_b32 v5, v2 offset:34588
	v_and_b32_e32 v4, 0xffff0000, v15
	s_waitcnt lgkmcnt(0)
	v_fmac_f32_e32 v1, v5, v4
	ds_read_b32 v5, v2 offset:34844
	ds_read_b32 v2, v2 offset:35100
	v_and_b32_e32 v4, 0xffff0000, v19
	s_waitcnt lgkmcnt(1)
	v_fmac_f32_e32 v1, v5, v4
	v_and_b32_e32 v4, 0xffff0000, v11
	s_waitcnt lgkmcnt(0)
	v_fmac_f32_e32 v1, v2, v4
	v_mul_f32_e32 v2, 0xbfb8aa3b, v1
	v_exp_f32_e32 v2, v2
	s_nop 0
	v_add_f32_e32 v2, 1.0, v2
	v_rcp_f32_e32 v2, v2
	s_nop 0
	v_mul_f32_e32 v1, v1, v2
	ds_write_b32 v22, v1 offset:28
	s_and_saveexec_b64 s[26:27], vcc
	s_cbranch_execz .LBB0_579
; __device__ __forceinline__ float bf2f(unsigned short b) { return __uint_as_float(((unsigned)b) << 16); }
; __device__ __forceinline__ float wave_scan_add_lds(volatile float* a, int t, float v) {
;   a[t] = v;
; #pragma unroll
;   for (int o = 1; o < 64; o <<= 1) { const float u = (t >= o) ? a[t - o] : 0.f; v += u; a[t] = v; }
;   return v;
; }
; __device__ __forceinline__ float wave_scan_max_lds(volatile float* a, int t, float v) {
;   a[t] = v;
; #pragma unroll
;   for (int o = 1; o < 64; o <<= 1) { const float u = (t >= o) ? a[t - o] : -3.0e38f; v = fmaxf(v, u); a[t] = v; }
;   return v;
; }
; __device__ __forceinline__ void ml_p1_item(const Params& p, int l, int item, char* ldsraw) {
;     ...
;   if (tid < 64) {
;     const int t = tid;
;     const float ip = bf2f(P[(size_t)(tokb + t) * PIN + C_ML + 512 + h]) + p.i_bias[l * 4 + h];
;     const float fp = bf2f(P[(size_t)(tokb + t) * PIN + C_ML + 516 + h]) + p.f_bias[l * 4 + h];
;     const float lf = fminf(fp, 0.f) - log1pf(__expf(-fabsf(fp)));
;     volatile float* sc = G + 64;
;     const float g = wave_scan_add_lds(sc, t, lf);
;     glast = sc[63];
;     const float a = glast - g + ip;
;     amax = wave_scan_max_lds(sc + 64, t, a);
;     amax = sc[64 + 63];
;     G[t] = __expf(a - amax);
	v_add_u32_e32 v1, s3, v0
	v_mov_b64_e32 v[4:5], s[28:29]
	v_mad_i64_i32 v[4:5], s[28:29], v1, s69, v[4:5]
	v_readlane_b32 s3, v255, 14
	s_lshl_b32 s28, s2, 1
	s_or_b32 s2, s2, s3
	s_ashr_i32 s3, s2, 31
	v_readlane_b32 s4, v252, 19
	s_mov_b32 s29, s89
	s_lshl_b64 s[2:3], s[2:3], 2
	v_readlane_b32 s16, v252, 31
	v_lshl_add_u64 v[4:5], v[4:5], 0, s[28:29]
	v_readlane_b32 s17, v252, 32
	s_add_u32 s28, s16, s2
	v_readlane_b32 s18, v252, 33
	s_addc_u32 s29, s17, s3
	v_readlane_b32 s19, v252, 34
	s_add_u32 s2, s18, s2
	global_load_ushort v2, v[4:5], off offset:3968
	global_load_dword v6, v3, s[28:29]
	global_load_ushort v1, v[4:5], off offset:3976
	s_addc_u32 s3, s19, s3
	global_load_dword v4, v3, s[2:3]
	s_mov_b32 s2, 0xbfb8aa3b
	v_mov_b32_e32 v7, 0
	v_readlane_b32 s5, v252, 20
	v_readlane_b32 s6, v252, 21
	v_readlane_b32 s7, v252, 22
	v_readlane_b32 s8, v252, 23
	v_readlane_b32 s9, v252, 24
	v_readlane_b32 s10, v252, 25
	v_readlane_b32 s11, v252, 26
	v_readlane_b32 s12, v252, 27
	v_readlane_b32 s13, v252, 28
	v_readlane_b32 s14, v252, 29
	v_readlane_b32 s15, v252, 30
	s_waitcnt vmcnt(1)
	v_lshlrev_b32_e32 v1, 16, v1
	s_waitcnt vmcnt(0)
	v_add_f32_e32 v1, v4, v1
	v_min_f32_e32 v8, 0, v1
	v_mul_f32_e64 v1, |v1|, s2
	v_exp_f32_e32 v1, v1
	s_mov_b32 s2, 0x3f2aaaab
	v_add_f32_e32 v9, 1.0, v1
	v_add_f32_e32 v4, -1.0, v9
	v_sub_f32_e32 v5, v4, v9
	v_add_f32_e32 v5, 1.0, v5
	v_sub_f32_e32 v4, v1, v4
	v_add_f32_e32 v10, v4, v5
	v_frexp_mant_f32_e32 v4, v9
	v_cmp_gt_f32_e32 vcc, s2, v4
	v_cvt_f64_f32_e32 v[4:5], v9
	v_frexp_exp_i32_f64_e32 v4, v[4:5]
	v_subbrev_co_u32_e32 v4, vcc, 0, v4, vcc
	v_sub_u32_e32 v5, 0, v4
	v_ldexp_f32 v9, v9, v5
	v_ldexp_f32 v5, v10, v5
	v_add_f32_e32 v10, -1.0, v9
	v_add_f32_e32 v11, 1.0, v10
	v_sub_f32_e32 v11, v9, v11
	v_add_f32_e32 v11, v5, v11
	v_add_f32_e32 v12, v10, v11
	v_sub_f32_e32 v10, v12, v10
	v_sub_f32_e32 v10, v11, v10
	v_add_f32_e32 v11, 1.0, v9
	v_add_f32_e32 v13, -1.0, v11
	v_sub_f32_e32 v9, v9, v13
	v_add_f32_e32 v5, v5, v9
	v_add_f32_e32 v9, v11, v5
	v_sub_f32_e32 v11, v9, v11
	v_sub_f32_e32 v5, v5, v11
	v_rcp_f32_e32 v11, v9
	v_cvt_f32_i32_e32 v4, v4
	s_mov_b32 s2, 0x3f317218
	v_mul_f32_e32 v13, v12, v11
	v_mul_f32_e32 v14, v9, v13
	v_fma_f32 v15, v13, v9, -v14
	v_fmac_f32_e32 v15, v13, v5
	v_add_f32_e32 v16, v14, v15
	v_sub_f32_e32 v17, v12, v16
	v_sub_f32_e32 v12, v12, v17
	v_sub_f32_e32 v14, v16, v14
	v_sub_f32_e32 v12, v12, v16
	v_add_f32_e32 v10, v10, v12
	v_sub_f32_e32 v12, v14, v15
	v_add_f32_e32 v10, v12, v10
	v_add_f32_e32 v12, v17, v10
	v_mul_f32_e32 v14, v11, v12
	v_mul_f32_e32 v15, v9, v14
	v_fma_f32 v9, v14, v9, -v15
	v_fmac_f32_e32 v9, v14, v5
	v_sub_f32_e32 v5, v17, v12
	v_add_f32_e32 v5, v10, v5
	v_add_f32_e32 v10, v15, v9
	v_sub_f32_e32 v16, v12, v10
	v_sub_f32_e32 v12, v12, v16
	v_sub_f32_e32 v15, v10, v15
	v_sub_f32_e32 v10, v12, v10
	v_add_f32_e32 v5, v5, v10
	v_sub_f32_e32 v9, v15, v9
	v_add_f32_e32 v5, v9, v5
	v_add_f32_e32 v9, v13, v14
	v_add_f32_e32 v5, v16, v5
	v_sub_f32_e32 v10, v9, v13
	v_mul_f32_e32 v5, v11, v5
	v_sub_f32_e32 v10, v14, v10
	v_add_f32_e32 v5, v10, v5
	v_mul_f32_e32 v13, 0x3f317218, v4
	v_add_f32_e32 v10, v9, v5
	v_fma_f32 v14, v4, s2, -v13
	v_mul_f32_e32 v11, v10, v10
	v_mov_b32_e32 v12, 0x3ecc95a3
	v_fmac_f32_e32 v14, 0xb102e308, v4
	v_sub_f32_e32 v4, v10, v9
	v_fmamk_f32 v12, v11, 0x3e9b6dac, v12
	v_sub_f32_e32 v4, v5, v4
	v_add_f32_e32 v5, v13, v14
	v_fmaak_f32 v12, v11, v12, 0x3f2aaada
	v_sub_f32_e32 v9, v5, v13
	v_ldexp_f32 v13, v10, 1
	v_mul_f32_e32 v10, v10, v11
	v_mul_f32_e32 v10, v10, v12
	v_add_f32_e32 v11, v13, v10
	v_sub_f32_e32 v12, v11, v13
	v_ldexp_f32 v4, v4, 1
	v_sub_f32_e32 v10, v10, v12
	v_add_f32_e32 v4, v4, v10
	v_add_f32_e32 v10, v11, v4
	v_sub_f32_e32 v11, v10, v11
	v_sub_f32_e32 v4, v4, v11
	v_add_f32_e32 v11, v5, v10
	v_sub_f32_e32 v12, v11, v5
	v_sub_f32_e32 v13, v11, v12
	v_sub_f32_e32 v9, v14, v9
	v_sub_f32_e32 v5, v5, v13
	v_sub_f32_e32 v10, v10, v12
	v_add_f32_e32 v5, v10, v5
	v_add_f32_e32 v10, v9, v4
	v_sub_f32_e32 v12, v10, v9
	v_sub_f32_e32 v13, v10, v12
	v_sub_f32_e32 v9, v9, v13
	v_sub_f32_e32 v4, v4, v12
	v_add_f32_e32 v5, v10, v5
	v_add_f32_e32 v4, v4, v9
	v_add_f32_e32 v9, v11, v5
	v_sub_f32_e32 v10, v9, v11
	v_sub_f32_e32 v5, v5, v10
	v_add_f32_e32 v4, v4, v5
	s_mov_b32 s2, 0x7f800000
	v_add_f32_e32 v4, v9, v4
	v_cmp_neq_f32_e32 vcc, s2, v1
	v_mov_b32_e32 v5, 0x7f800000
	s_mov_b32 s2, 0x33800000
	v_cndmask_b32_e32 v4, v5, v4, vcc
	v_cmp_ngt_f32_e32 vcc, -1.0, v1
	v_mov_b32_e32 v5, 0x7fc00000
	v_mov_b32_e32 v9, 0
	v_cndmask_b32_e32 v4, v5, v4, vcc
	v_cmp_neq_f32_e32 vcc, -1.0, v1
	v_mov_b32_e32 v5, 0xff800000
	s_nop 0
	v_cndmask_b32_e32 v4, v5, v4, vcc
	v_cmp_lt_f32_e64 vcc, |v1|, s2
	s_mov_b64 s[2:3], src_shared_base
	v_mov_b32_e32 v5, s3
	v_cndmask_b32_e32 v1, v4, v1, vcc
	v_sub_f32_e32 v8, v8, v1
	v_lshl_add_u32 v1, v0, 2, 0
	s_nop 1
	v_add_f32_dpp v8, v8, v8 row_shr:1 row_mask:0xf bank_mask:0xf
	s_nop 1
	v_add_f32_dpp v8, v8, v8 row_shr:2 row_mask:0xf bank_mask:0xf
	s_nop 1
	v_add_f32_dpp v8, v8, v8 row_shr:4 row_mask:0xf bank_mask:0xf
	s_nop 1
	v_add_f32_dpp v8, v8, v8 row_shr:8 row_mask:0xf bank_mask:0xf
	s_nop 1
	v_add_f32_dpp v8, v8, v8 row_bcast:15 row_mask:0xa bank_mask:0xf
	s_nop 1
	v_add_f32_dpp v8, v8, v8 row_bcast:31 row_mask:0xc bank_mask:0xf
	s_nop 1
	v_readlane_b32 s2, v8, 63
	v_lshlrev_b32_e32 v2, 16, v2
	v_add_f32_e32 v2, v6, v2
	v_mov_b32_e32 v16, s2
	v_sub_f32_e32 v6, v16, v8
	v_add_f32_e32 v2, v2, v6
	v_mov_b32_e32 v6, v2
	s_nop 1
	v_max_f32_dpp v6, v6, v6 row_shr:1 row_mask:0xf bank_mask:0xf
	s_nop 1
	v_max_f32_dpp v6, v6, v6 row_shr:2 row_mask:0xf bank_mask:0xf
	s_nop 1
	v_max_f32_dpp v6, v6, v6 row_shr:4 row_mask:0xf bank_mask:0xf
	s_nop 1
	v_max_f32_dpp v6, v6, v6 row_shr:8 row_mask:0xf bank_mask:0xf
	s_nop 1
	v_max_f32_dpp v6, v6, v6 row_bcast:15 row_mask:0xa bank_mask:0xf
	s_nop 1
	v_max_f32_dpp v6, v6, v6 row_bcast:31 row_mask:0xc bank_mask:0xf
	s_nop 1
	v_readlane_b32 s2, v6, 63
	s_nop 1
	v_mov_b32_e32 v17, s2
	v_sub_f32_e32 v2, v2, v17
	v_mul_f32_e32 v2, 0x3fb8aa3b, v2
	v_exp_f32_e32 v2, v2
	s_nop 0
	ds_write_b32 v1, v2 offset:24832
